# XCD-local grid barriers: L1 invalidate issued before the wait (overlapped with polling), leader releases before invalidating; K-row loads of the WY-factor phase batched
# speedup vs baseline: 1.0584x; 1.0142x over previous
.LBB0_27:
	s_or_b64 exec, exec, s[4:5]
	v_cvt_f32_u32_e32 v6, v4
	s_waitcnt vmcnt(0)
	v_readfirstlane_b32 s4, v5
	v_sub_u32_e32 v5, 0, v4
	v_rcp_iflag_f32_e32 v6, v6
	v_add_u32_e32 v7, s4, v3
	v_mul_f32_e32 v6, 0x4f7ffffe, v6
	v_cvt_u32_f32_e32 v6, v6
	v_mul_lo_u32 v3, v5, v6
	v_mul_hi_u32 v3, v6, v3
	v_add_u32_e32 v3, v6, v3
	v_mul_hi_u32 v3, v7, v3
	v_mul_lo_u32 v5, v3, v4
	v_sub_u32_e32 v5, v7, v5
	v_add_u32_e32 v6, 1, v3
	v_cmp_ge_u32_e32 vcc, v5, v4
	s_nop 1
	v_cndmask_b32_e32 v3, v3, v6, vcc
	v_sub_u32_e32 v6, v5, v4
	v_cndmask_b32_e32 v5, v5, v6, vcc
	v_add_u32_e32 v6, 1, v3
	v_cmp_ge_u32_e32 vcc, v5, v4
	v_add_u32_e32 v5, 1, v7
	s_nop 0
	v_cndmask_b32_e32 v3, v3, v6, vcc
	v_mul_lo_u32 v6, v4, v3
	v_add_u32_e32 v4, v6, v4
	v_cmp_ne_u32_e32 vcc, v5, v4
	s_and_saveexec_b64 s[4:5], vcc
	s_xor_b64 s[4:5], exec, s[4:5]
	s_cbranch_execz .LBB0_41
	v_readlane_b32 s100, v255, 40
	s_cmp_eq_u32 s100, 1
	s_cbranch_scc0 .Lnl_glob
	s_mul_hi_u32 s101, s17, 0x1999999a
	s_mul_i32 s101, s101, 10
	s_sub_i32 s101, s17, s101
	s_lshr_b32 s100, 0x395, s101
	s_and_b32 s100, s100, 1
	s_cmp_eq_u32 s101, 1
	s_cbranch_scc0 .Lnl_dec
	s_cmp_gt_u32 s17, 1
	s_cselect_b32 s100, 1, 0
	s_branch .Lnl_dec
.Lnl_glob:
	s_mov_b32 s100, 0
.Lnl_dec:
	s_cmp_eq_u32 s100, 1
	s_cbranch_scc0 .Lnl_noinv
	buffer_inv sc1
.Lnl_noinv:
	v_readlane_b32 s6, v253, 8
	v_readlane_b32 s7, v253, 9
	s_waitcnt lgkmcnt(0)
	s_nop 3
	global_load_dword v2, v131, s[6:7] sc1
	s_waitcnt vmcnt(0)
	v_cmp_eq_u32_e32 vcc, v2, v3
	s_and_saveexec_b64 s[6:7], vcc
	s_cbranch_execz .LBB0_40
	s_mov_b32 s13, 1
	s_mov_b64 s[10:11], 0
	s_branch .LBB0_31

.LBB0_40:
	s_or_b64 exec, exec, s[6:7]
	s_waitcnt vmcnt(0)
	s_cmp_eq_u32 s100, 1
	s_cbranch_scc1 .Lnl_done
	buffer_inv sc1
.Lnl_done:
	s_waitcnt vmcnt(0)
.LBB0_41:
	s_andn2_saveexec_b64 s[4:5], s[4:5]
	s_cbranch_execz .LBB0_61
	v_readlane_b32 s6, v255, 40
	s_cmp_eq_u32 s6, 1
	s_cbranch_scc0 .Lbar_global
	s_mul_hi_u32 s6, s17, 0x1999999a
	s_mul_i32 s6, s6, 10
	s_sub_i32 s6, s17, s6
	s_lshr_b32 s7, 0x395, s6
	s_bitcmp1_b32 s7, 0
	s_cbranch_scc1 .Lbar_local
	s_cmp_eq_u32 s6, 1
	s_cbranch_scc0 .Lbar_global
	s_cmp_gt_u32 s17, 1
	s_cbranch_scc0 .Lbar_global
.Lbar_local:
	s_waitcnt vmcnt(0) lgkmcnt(0)
	v_mov_b32_e32 v2, 1
	v_readlane_b32 s4, v253, 8
	v_readlane_b32 s5, v253, 9
	s_nop 4
	global_atomic_add v131, v2, s[4:5]
	buffer_inv sc1
	s_waitcnt vmcnt(0)
	s_branch .LBB0_61

.LBB0_319:
	s_and_b64 vcc, exec, s[10:11]
	s_cbranch_vccz .LBB0_314
	v_readlane_b32 s10, v253, 20
	v_readlane_b32 s11, v253, 21
	v_add_u32_e32 v2, s22, v118
	s_lshl_b32 s92, s27, 8
	v_mov_b64_e32 v[6:7], s[10:11]
	v_mad_i64_i32 v[2:3], s[10:11], v2, s12, v[6:7]
	v_lshl_add_u64 v[2:3], v[2:3], 0, s[92:93]
	v_lshlrev_b32_e32 v50, 2, v22
	v_mov_b32_e32 v51, v131
	v_lshl_add_u64 v[2:3], v[2:3], 0, v[50:51]
	global_load_dwordx4 v[220:223], v[2:3], off offset:1024
	v_add_u32_e32 v2, s22, v119
	v_mad_i64_i32 v[2:3], s[10:11], v2, s12, v[6:7]
	v_lshl_add_u64 v[2:3], v[2:3], 0, s[92:93]
	v_lshl_add_u64 v[2:3], v[2:3], 0, v[50:51]
	global_load_dwordx4 v[224:227], v[2:3], off offset:1024
	v_add_u32_e32 v2, s22, v120
	v_mad_i64_i32 v[2:3], s[10:11], v2, s12, v[6:7]
	v_lshl_add_u64 v[2:3], v[2:3], 0, s[92:93]
	v_lshl_add_u64 v[2:3], v[2:3], 0, v[50:51]
	global_load_dwordx4 v[228:231], v[2:3], off offset:1024
	v_add_u32_e32 v2, s22, v121
	v_mad_i64_i32 v[2:3], s[10:11], v2, s12, v[6:7]
	v_lshl_add_u64 v[2:3], v[2:3], 0, s[92:93]
	v_lshl_add_u64 v[2:3], v[2:3], 0, v[50:51]
	global_load_dwordx4 v[232:235], v[2:3], off offset:1024
	s_and_saveexec_b64 s[10:11], s[28:29]
	s_cbranch_execz .LBB0_322
	s_cmp_eq_u32 s25, 0
	s_cselect_b64 vcc, -1, 0
	v_cndmask_b32_e32 v2, v58, v19, vcc
	v_or_b32_e32 v2, s22, v2
	s_lshl_b32 s64, s25, 2
	v_lshl_or_b32 v2, v2, 3, s64
	v_or_b32_e32 v2, s27, v2
	v_mov_b32_e32 v3, v131
	v_readlane_b32 s64, v253, 22
	v_lshlrev_b64 v[2:3], 2, v[2:3]
	v_readlane_b32 s65, v253, 23
	v_add_u32_e32 v6, -2, v198
	s_nop 0
	v_lshl_add_u64 v[4:5], s[64:65], 0, v[2:3]
	global_load_dword v4, v[4:5], off
	v_readlane_b32 s64, v253, 50
	v_readlane_b32 s65, v253, 51
	s_nop 1
	v_lshl_add_u64 v[2:3], s[64:65], 0, v[2:3]
	global_load_dword v2, v[2:3], off
	v_and_b32_e32 v3, 64, v198
	v_add_u32_e32 v5, -1, v198
	v_cmp_lt_i32_e32 vcc, v5, v3
	v_readlane_b32 s64, v255, 7
	v_readlane_b32 s65, v255, 8
	v_cndmask_b32_e32 v5, v5, v198, vcc
	v_lshlrev_b32_e32 v5, 2, v5
	v_cmp_lt_i32_e32 vcc, v6, v3
	s_waitcnt vmcnt(1)
	ds_bpermute_b32 v5, v5, v4
	v_cndmask_b32_e32 v6, v6, v198, vcc
	v_lshlrev_b32_e32 v6, 2, v6
	s_waitcnt lgkmcnt(0)
	v_add_f32_e32 v5, v4, v5
	v_cndmask_b32_e64 v4, v5, v4, s[30:31]
	ds_bpermute_b32 v5, v6, v4
	v_add_u32_e32 v6, -4, v198
	v_cmp_lt_i32_e32 vcc, v6, v3
	s_waitcnt lgkmcnt(0)
	v_add_f32_e32 v5, v4, v5
	v_cndmask_b32_e32 v6, v6, v198, vcc
	v_lshlrev_b32_e32 v6, 2, v6
	v_cndmask_b32_e64 v4, v5, v4, s[34:35]
	ds_bpermute_b32 v5, v6, v4
	v_add_u32_e32 v6, -8, v198
	v_cmp_lt_i32_e32 vcc, v6, v3
	s_waitcnt lgkmcnt(0)
	v_add_f32_e32 v5, v4, v5
	v_cndmask_b32_e32 v6, v6, v198, vcc
	v_lshlrev_b32_e32 v6, 2, v6
	v_cndmask_b32_e64 v4, v5, v4, s[88:89]
	ds_bpermute_b32 v5, v6, v4
	v_add_u32_e32 v6, -16, v198
	v_cmp_lt_i32_e32 vcc, v6, v3
	s_waitcnt lgkmcnt(0)
	v_add_f32_e32 v5, v4, v5
	v_cndmask_b32_e32 v6, v6, v198, vcc
	v_lshlrev_b32_e32 v6, 2, v6
	v_cndmask_b32_e64 v4, v5, v4, s[94:95]
	ds_bpermute_b32 v5, v6, v4
	v_subrev_u32_e32 v6, 32, v198
	v_cmp_lt_i32_e32 vcc, v6, v3
	s_waitcnt lgkmcnt(0)
	v_add_f32_e32 v5, v4, v5
	v_cndmask_b32_e32 v3, v6, v198, vcc
	v_lshlrev_b32_e32 v3, 2, v3
	v_cndmask_b32_e64 v4, v5, v4, s[96:97]
	ds_bpermute_b32 v3, v3, v4
	s_waitcnt lgkmcnt(0)
	v_add_f32_e32 v3, v4, v3
	v_cndmask_b32_e64 v3, v3, v4, s[64:65]
	v_mul_f32_e32 v4, 0x3fb8aa3b, v3
	v_exp_f32_e32 v4, v4
	ds_write_b32 v59, v3
	ds_write_b32 v60, v4
	s_waitcnt vmcnt(0)
	ds_write_b32 v61, v2
.LBB0_322:
	s_or_b64 exec, exec, s[10:11]
	s_waitcnt vmcnt(0)
	ds_write2_b32 v178, v220, v221 offset1:1
	ds_write2_b32 v178, v222, v223 offset0:2 offset1:3
	ds_write2_b32 v179, v224, v225 offset1:1
	ds_write2_b32 v179, v226, v227 offset0:2 offset1:3
	ds_write2_b32 v180, v228, v229 offset1:1
	ds_write2_b32 v180, v230, v231 offset0:2 offset1:3
	ds_write2_b32 v181, v232, v233 offset1:1
	ds_write2_b32 v181, v234, v235 offset0:2 offset1:3
	v_mov_b32_e32 v17, 0
	v_mov_b32_e32 v16, v17
	v_mov_b32_e32 v15, v17
	v_mov_b32_e32 v14, v17
	v_mov_b32_e32 v13, v17
	v_mov_b32_e32 v12, v17
	v_mov_b32_e32 v11, v17
	v_mov_b32_e32 v10, v17
	v_mov_b32_e32 v9, v17
	v_mov_b32_e32 v8, v17
	v_mov_b32_e32 v7, v17
	v_mov_b32_e32 v6, v17
	v_mov_b32_e32 v5, v17
	v_mov_b32_e32 v4, v17
	v_mov_b32_e32 v3, v17
	v_mov_b32_e32 v2, v17
	s_waitcnt lgkmcnt(0)
	s_barrier
	s_mov_b64 s[10:11], exec
	v_readlane_b32 s64, v255, 9
	v_readlane_b32 s65, v255, 10
	s_and_b64 s[64:65], s[10:11], s[64:65]
	s_mov_b64 exec, s[64:65]
	s_cbranch_execz .LBB0_325
	s_cmp_eq_u32 s25, 0
	s_cselect_b64 vcc, -1, 0
	v_cndmask_b32_e32 v2, v63, v62, vcc
	v_mad_u64_u32 v[52:53], s[66:67], v2, s85, v[18:19]
	v_cndmask_b32_e32 v2, v65, v64, vcc
	v_mad_u32_u24 v47, v2, s85, v18
	v_mov_b32_e32 v2, 0
	s_mov_b32 s64, 0
	v_mov_b32_e32 v3, v2
	v_mov_b32_e32 v4, v2
	v_mov_b32_e32 v5, v2
	v_mov_b32_e32 v6, v2
	v_mov_b32_e32 v7, v2
	v_mov_b32_e32 v8, v2
	v_mov_b32_e32 v9, v2
	v_mov_b32_e32 v10, v2
	v_mov_b32_e32 v11, v2
	v_mov_b32_e32 v12, v2
	v_mov_b32_e32 v13, v2
	v_mov_b32_e32 v14, v2
	v_mov_b32_e32 v15, v2
	v_mov_b32_e32 v16, v2
	v_mov_b32_e32 v17, v2
